# B1 prep: LoRA weight fragments fetched once per phase (LDS-DMA into per-wave LDS area + AGPRs) instead of 4 dependent L2 round trips per item
# speedup vs baseline: 1.0260x; 1.0260x over previous
.LBB0_323:
	s_or_b64 exec, exec, s[0:1]
	s_add_i32 s24, 0, 0x24008
	s_mov_b64 s[0:1], src_shared_base
	s_cmp_lg_u32 s24, -1
	s_cselect_b32 s0, s24, 0
	s_cselect_b32 s1, s1, 0
	v_mov_b32_e32 v2, s0
	v_mov_b32_e32 v3, s1
	s_waitcnt lgkmcnt(0)
	s_barrier
	flat_load_dword v206, v[2:3] sc0 sc1
	s_waitcnt vmcnt(0)
	s_movk_i32 s0, 0x84c
	s_waitcnt lgkmcnt(0)
	v_cmp_gt_i32_e32 vcc, s0, v206
	s_and_saveexec_b64 s[46:47], vcc
	s_cbranch_execz .LBB0_499
	s_lshl_b64 s[0:1], s[36:37], 15
	v_lshlrev_b64 v[0:1], 6, v[0:1]
	v_lshl_add_u64 v[0:1], v[0:1], 0, s[0:1]
	v_readlane_b32 s0, v214, 33
	v_lshlrev_b64 v[0:1], 1, v[0:1]
	v_readlane_b32 s1, v214, 34
	s_mov_b64 s[22:23], s[36:37]
	s_lshl_b32 s37, s22, 5
	v_lshl_add_u64 v[126:127], s[0:1], 0, v[0:1]
	v_readlane_b32 s0, v214, 35
	v_readlane_b32 s1, v214, 36
	s_lshl_b64 s[30:31], s[22:23], 3
	s_lshl_b64 s[60:61], s[22:23], 7
	v_lshl_add_u64 v[128:129], s[0:1], 0, v[0:1]
	s_lshl_b32 s0, s22, 8
	s_ashr_i32 s1, s0, 31
	s_lshl_b32 s72, s22, 2
	s_lshl_b32 s33, s22, 7
	s_lshl_b64 s[0:1], s[0:1], 2
	s_add_u32 s34, s12, s0
	s_addc_u32 s35, s13, s1
	s_mov_b64 s[0:1], s[54:55]
	s_mov_b64 s[28:29], s[46:47]
	v_readlane_b32 s40, v213, 42
	s_mul_i32 s20, s22, 0xd0000
	v_readlane_b32 s48, v213, 50
	s_mul_hi_i32 s2, s22, 0xd0000
	v_readlane_b32 s49, v213, 51
	v_readlane_b32 s54, v213, 56
	v_readlane_b32 s55, v213, 57
	s_add_u32 s64, s48, s20
	v_readlane_b32 s52, v213, 54
	s_mov_b64 s[54:55], s[0:1]
	s_addc_u32 s65, s49, s2
	s_mul_i32 s1, s22, 0x1e000
	v_readlane_b32 s2, v213, 36
	v_readlane_b32 s53, v213, 55
	s_mul_hi_i32 s0, s22, 0x1e000
	s_add_u32 s52, s2, s1
	v_readlane_b32 s1, v213, 37
	v_readlane_b32 s46, v213, 48
	s_addc_u32 s53, s1, s0
	s_mul_i32 s1, s22, 0x1e0000
	v_readlane_b32 s47, v213, 49
	s_mul_hi_i32 s0, s22, 0x1e0000
	s_add_u32 s20, s46, s1
	s_addc_u32 s21, s47, s0
	v_writelane_b32 v212, s20, 45
	v_readlane_b32 s2, v213, 62
	v_readlane_b32 s50, v213, 52
	v_writelane_b32 v212, s21, 46
	s_add_u32 s20, s92, s1
	s_addc_u32 s21, s93, s0
	v_writelane_b32 v212, s20, 43
	s_mul_i32 s1, s22, 0xd000
	s_mul_hi_i32 s0, s22, 0xd000
	v_writelane_b32 v212, s21, 44
	s_add_u32 s20, s2, s1
	v_readlane_b32 s1, v213, 63
	v_readlane_b32 s51, v213, 53
	s_addc_u32 s21, s1, s0
	s_mov_b64 s[50:51], s[34:35]
	s_mov_b64 s[48:49], s[30:31]
	s_mov_b32 s66, s60
	s_mov_b32 s67, s61
	s_mov_b64 s[46:47], s[28:29]
	v_writelane_b32 v212, s20, 47
	v_mov_b32_e32 v205, 0
	s_mov_b64 s[58:59], 0
	v_readlane_b32 s41, v213, 43
	v_readlane_b32 s42, v213, 44
	v_readlane_b32 s43, v213, 45
	v_readlane_b32 s44, v213, 46
	v_readlane_b32 s45, v213, 47
	v_writelane_b32 v212, s21, 48
	v_lshrrev_b32_e32 v218, 6, v133
	v_and_b32_e32 v217, 15, v192
	v_readfirstlane_b32 s0, v218
	v_lshlrev_b32_e32 v217, 7, v217
	v_lshrrev_b32_e32 v219, 4, v192
	v_lshl_add_u32 v217, v219, 4, v217
	s_mul_i32 s0, s0, 0x3000
	s_addk_i32 s0, 0x6000
	v_mov_b32_e32 v218, v217
	v_mov_b32_e32 v219, 0
	v_lshl_add_u64 v[218:219], v[126:127], 0, v[218:219]
	s_add_i32 m0, s0, 0x0
	s_nop 0
	global_load_lds_dwordx4 v[218:219], off
	s_add_i32 m0, s0, 0x7c0
	s_nop 0
	global_load_lds_dwordx4 v[218:219], off offset:64
	s_add_i32 m0, s0, 0x800
	s_nop 0
	global_load_lds_dwordx4 v[218:219], off offset:2048
	s_add_i32 m0, s0, 0xfc0
	s_nop 0
	global_load_lds_dwordx4 v[218:219], off offset:2112
	v_add_co_u32_e32 v218, vcc, 0x1000, v218
	s_nop 1
	v_addc_co_u32_e32 v219, vcc, 0, v219, vcc
	s_add_i32 m0, s0, 0x2000
	s_nop 0
	global_load_lds_dwordx4 v[218:219], off
	s_add_i32 m0, s0, 0x27c0
	s_nop 0
	global_load_lds_dwordx4 v[218:219], off offset:64
	global_load_dwordx4 a[0:3], v[218:219], off offset:2048
	global_load_dwordx4 a[8:11], v[218:219], off offset:2112
	v_mov_b32_e32 v218, v217
	v_mov_b32_e32 v219, 0
	v_lshl_add_u64 v[218:219], v[128:129], 0, v[218:219]
	s_add_i32 m0, s0, 0x400
	s_nop 0
	global_load_lds_dwordx4 v[218:219], off
	s_add_i32 m0, s0, 0xbc0
	s_nop 0
	global_load_lds_dwordx4 v[218:219], off offset:64
	s_add_i32 m0, s0, 0xc00
	s_nop 0
	global_load_lds_dwordx4 v[218:219], off offset:2048
	s_add_i32 m0, s0, 0x13c0
	s_nop 0
	global_load_lds_dwordx4 v[218:219], off offset:2112
	v_add_co_u32_e32 v218, vcc, 0x1000, v218
	s_nop 1
	v_addc_co_u32_e32 v219, vcc, 0, v219, vcc
	s_add_i32 m0, s0, 0x2400
	s_nop 0
	global_load_lds_dwordx4 v[218:219], off
	s_add_i32 m0, s0, 0x2bc0
	s_nop 0
	global_load_lds_dwordx4 v[218:219], off offset:64
	global_load_dwordx4 a[4:7], v[218:219], off offset:2048
	global_load_dwordx4 a[12:15], v[218:219], off offset:2112
	v_lshlrev_b32_e32 v217, 4, v192
	v_add_u32_e32 v217, s0, v217
	s_branch .LBB0_326

.Lpc_done:
	v_mul_u32_u24_e32 v2, 0x48, v98
	v_lshlrev_b32_e32 v2, 1, v2
	v_lshlrev_b32_e32 v3, 4, v207
	v_add3_u32 v2, 0, v2, v3
	s_waitcnt lgkmcnt(0)
	s_barrier
	ds_read_b128 v[32:35], v2
	ds_read_b128 v[24:27], v2 offset:64
	ds_read_b128 v[28:31], v2 offset:2304
	ds_read_b128 v[20:23], v2 offset:2368
	v_ashrrev_i32_e32 v148, 6, v130
	s_movk_i32 s0, 0x3fff
	v_ashrrev_i32_e32 v135, 31, v134
	v_cmp_lt_i32_e32 vcc, s0, v134
	v_ashrrev_i32_e32 v149, 31, v148
	s_and_saveexec_b64 s[0:1], vcc
	s_xor_b64 s[0:1], exec, s[0:1]
	v_lshl_add_u64 v[78:79], v[134:135], 3, v[148:149]
	s_andn2_saveexec_b64 s[0:1], s[0:1]
	v_ashrrev_i32_e32 v2, 8, v132
	v_and_b32_e32 v2, -8, v2
	v_add_u32_e32 v2, v148, v2
	v_ashrrev_i32_e32 v3, 31, v2
	v_lshlrev_b64 v[78:79], 11, v[2:3]
	s_movk_i32 s2, 0x7ff
	v_and_or_b32 v78, v134, s2, v78
	s_or_b64 exec, exec, s[0:1]
	v_lshlrev_b32_e32 v6, 1, v0
	v_mov_b32_e32 v7, v65
	v_lshl_add_u64 v[160:161], v[126:127], 0, v[6:7]
	v_lshlrev_b32_e32 v8, 7, v98
	v_mov_b32_e32 v9, v65
	v_lshl_add_u64 v[74:75], v[160:161], 0, v[8:9]
	ds_read_b128 v[2:5], v217 offset:0
	v_lshl_add_u64 v[162:163], v[128:129], 0, v[6:7]
	v_lshl_add_u64 v[76:77], v[162:163], 0, v[8:9]
	ds_read_b128 v[6:9], v217 offset:1024
	ds_read_b128 v[12:15], v217 offset:2048
	ds_read_b128 v[16:19], v217 offset:3072
	v_lshlrev_b32_e32 v64, 2, v207
	v_or_b32_e32 v10, v98, v1
	v_add_u32_e32 v11, 0xffffc000, v134
	v_mov_b64_e32 v[0:1], s[64:65]
	v_lshl_add_u32 v208, v64, 2, v204
	v_cmp_ne_u32_e64 s[0:1], 0, v10
	v_mad_i64_i32 v[158:159], s[20:21], v11, s86, v[0:1]
	v_or_b32_e32 v80, v64, v150
	s_waitcnt lgkmcnt(0)
	v_mfma_f32_16x16x32_bf16 v[52:55], v[6:9], v[28:31], 0
	v_mfma_f32_16x16x32_bf16 v[36:39], v[2:5], v[32:35], 0
	ds_read_b128 v[0:3], v208 offset:8192
	ds_read_b128 v[48:51], v208 offset:8448
	ds_read_b128 v[8:11], v208 offset:8704
	ds_read_b128 v[40:43], v208 offset:8960
	s_nop 0
	v_mfma_f32_16x16x32_bf16 v[66:69], v[12:15], v[24:27], v[36:39]
	ds_read_b128 v[4:7], v208 offset:9216
	ds_read_b128 v[12:15], v208 offset:9472
	ds_read_b128 v[44:47], v208 offset:9728
	ds_read_b128 v[36:39], v208 offset:9984
	s_waitcnt lgkmcnt(8)
	v_mfma_f32_16x16x32_bf16 v[52:55], v[16:19], v[20:23], v[52:55]
	s_and_saveexec_b64 s[20:21], s[40:41]
	s_xor_b64 s[20:21], exec, s[20:21]
	s_cbranch_execz .LBB0_452
	v_ashrrev_i32_e32 v81, 31, v80
	v_lshl_add_u64 v[60:61], v[80:81], 2, v[158:159]
	global_load_dwordx4 v[16:19], v[60:61], off
	global_load_dwordx4 v[56:59], v[60:61], off offset:2048
	v_add_co_u32_e32 v60, vcc, 0x1000, v60
	s_nop 1
	v_addc_co_u32_e32 v61, vcc, 0, v61, vcc
	global_load_dwordx4 v[60:63], v[60:61], off

.LBB0_456:
	s_or_b64 exec, exec, s[20:21]
	s_waitcnt lgkmcnt(7)
	v_add_f32_e32 v0, v66, v0
	v_readlane_b32 s0, v214, 6
	v_mul_f32_e64 v66, |v0|, s87
	v_readlane_b32 s1, v214, 7
	v_exp_f32_e32 v66, v66
	s_movk_i32 s2, 0x600
	v_mov_b64_e32 v[80:81], s[0:1]
	v_mad_u64_u32 v[80:81], s[0:1], v78, s2, v[80:81]
	v_mov_b32_e32 v78, v81
	v_mad_u64_u32 v[78:79], s[0:1], v79, s2, v[78:79]
	v_add_f32_e32 v66, 1.0, v66
	s_mov_b32 s2, 0x800000
	v_cmp_gt_f32_e32 vcc, s2, v66
	s_mov_b32 s20, 0x3f317217
	s_mov_b32 s21, 0x7f800000
	v_cndmask_b32_e64 v82, 0, 32, vcc
	v_ldexp_f32 v66, v66, v82
	v_log_f32_e32 v66, v66
	v_max_f32_e64 v0, -v0, 0
	v_add_f32_e32 v1, v67, v1
	s_waitcnt lgkmcnt(6)
	v_add_f32_e32 v48, v52, v48
	v_mul_f32_e32 v83, 0x3f317217, v66
	v_fma_f32 v83, v66, s20, -v83
	v_fmac_f32_e32 v83, 0x3377d1cf, v66
	v_fmac_f32_e32 v83, 0x3f317217, v66
	v_cmp_lt_f32_e64 s[0:1], |v66|, s21
	v_mul_f32_e32 v48, 0xbfb8aa3b, v48
	v_add_f32_e32 v49, v53, v49
	v_cndmask_b32_e64 v66, v66, v83, s[0:1]
	v_cndmask_b32_e32 v83, 0, v197, vcc
	v_sub_f32_e32 v66, v66, v83
	v_add_f32_e32 v0, v0, v66
	v_mul_f32_e64 v66, |v1|, s87
	v_exp_f32_e32 v66, v66
	v_exp_f32_e32 v48, v48
	v_mul_f32_e32 v49, 0xbfb8aa3b, v49
	v_exp_f32_e32 v49, v49
	v_add_f32_e32 v52, 1.0, v66
	v_cmp_gt_f32_e32 vcc, s2, v52
	v_add_f32_e32 v48, 1.0, v48
	v_rcp_f32_e32 v152, v48
	v_cndmask_b32_e64 v66, 0, 32, vcc
	v_ldexp_f32 v52, v52, v66
	v_log_f32_e32 v52, v52
	v_add_f32_e32 v48, 1.0, v49
	v_add_f32_e32 v2, v68, v2
	v_max_f32_e64 v1, -v1, 0
	v_mul_f32_e32 v66, 0x3f317217, v52
	v_fma_f32 v66, v52, s20, -v66
	v_fmac_f32_e32 v66, 0x3377d1cf, v52
	v_fmac_f32_e32 v66, 0x3f317217, v52
	v_cmp_lt_f32_e64 s[0:1], |v52|, s21
	v_rcp_f32_e32 v153, v48
	v_mul_f32_e64 v48, |v2|, s87
	v_cndmask_b32_e64 v52, v52, v66, s[0:1]
	v_cndmask_b32_e32 v66, 0, v197, vcc
	v_sub_f32_e32 v52, v52, v66
	v_add_f32_e32 v1, v1, v52
	v_exp_f32_e32 v52, v48
	v_mov_b32_e32 v81, v78
	v_lshlrev_b32_e32 v78, 16, v72
	v_and_b32_e32 v79, 0xffff0000, v72
	s_waitcnt vmcnt(1)
	v_pk_add_f32 v[48:49], v[56:57], v[78:79] neg_lo:[0,1] neg_hi:[0,1]
	v_max_f32_e64 v2, -v2, 0
	s_waitcnt lgkmcnt(1)
	v_pk_fma_f32 v[168:169], v[44:45], v[48:49], v[78:79]
	v_add_f32_e32 v48, 1.0, v52
	v_cmp_gt_f32_e32 vcc, s2, v48
	v_pk_add_f32 v[44:45], v[152:153], -1.0 op_sel_hi:[1,0]
	v_add_f32_e32 v3, v69, v3
	v_cndmask_b32_e64 v49, 0, 32, vcc
	v_ldexp_f32 v48, v48, v49
	v_log_f32_e32 v48, v48
	v_pk_fma_f32 v[40:41], v[40:41], v[44:45], 1.0 op_sel_hi:[1,1,0]
	v_cndmask_b32_e32 v45, 0, v197, vcc
	v_sub_f32_e32 v0, -0.5, v0
	v_mul_f32_e32 v44, 0x3f317217, v48
	v_fma_f32 v44, v48, s20, -v44
	v_fmac_f32_e32 v44, 0x3377d1cf, v48
	v_fmac_f32_e32 v44, 0x3f317217, v48
	v_cmp_lt_f32_e64 s[0:1], |v48|, s21
	v_sub_f32_e32 v1, -0.5, v1
	v_mul_f32_e32 v0, 0x3fb8aa3b, v0
	v_cndmask_b32_e64 v44, v48, v44, s[0:1]
	v_sub_f32_e32 v44, v44, v45
	v_add_f32_e32 v2, v2, v44
	v_mul_f32_e64 v44, |v3|, s87
	v_exp_f32_e32 v44, v44
	v_max_f32_e64 v3, -v3, 0
	v_add_f32_e32 v45, v54, v50
	v_mul_f32_e32 v45, 0xbfb8aa3b, v45
	v_add_f32_e32 v44, 1.0, v44
	v_cmp_gt_f32_e32 vcc, s2, v44
	v_exp_f32_e32 v45, v45
	v_sub_f32_e32 v2, -0.5, v2
	v_cndmask_b32_e64 v48, 0, 32, vcc
	v_ldexp_f32 v44, v44, v48
	v_log_f32_e32 v44, v44
	v_mul_f32_e32 v1, 0x3fb8aa3b, v1
	v_mul_f32_e32 v2, 0x3fb8aa3b, v2
	v_exp_f32_e32 v0, v0
	v_mul_f32_e32 v48, 0x3f317217, v44
	v_fma_f32 v48, v44, s20, -v48
	v_fmac_f32_e32 v48, 0x3377d1cf, v44
	v_fmac_f32_e32 v48, 0x3f317217, v44
	v_cmp_lt_f32_e64 s[0:1], |v44|, s21
	v_exp_f32_e32 v1, v1
	v_exp_f32_e32 v2, v2
	v_cndmask_b32_e64 v44, v44, v48, s[0:1]
	v_cndmask_b32_e32 v48, 0, v197, vcc
	v_sub_f32_e32 v44, v44, v48
	v_add_f32_e32 v3, v3, v44
	v_add_f32_e32 v44, v55, v51
	v_mul_f32_e32 v44, 0xbfb8aa3b, v44
	v_exp_f32_e32 v44, v44
	v_sub_f32_e32 v3, -0.5, v3
	v_mul_f32_e32 v3, 0x3fb8aa3b, v3
	v_exp_f32_e32 v3, v3
	v_add_f32_e32 v45, 1.0, v45
	v_add_f32_e32 v44, 1.0, v44
	v_rcp_f32_e32 v156, v45
	v_rcp_f32_e32 v157, v44
	v_lshlrev_b32_e32 v72, 16, v73
	v_and_b32_e32 v73, 0xffff0000, v73
	v_mul_f32_e32 v0, 0xbfb8aa3b, v0
	v_mul_f32_e32 v1, 0xbfb8aa3b, v1
	v_mul_f32_e32 v2, 0xbfb8aa3b, v2
	v_mul_f32_e32 v3, 0xbfb8aa3b, v3
	v_pk_add_f32 v[44:45], v[58:59], v[72:73] neg_lo:[0,1] neg_hi:[0,1]
	v_lshlrev_b32_e32 v82, 16, v70
	v_and_b32_e32 v83, 0xffff0000, v70
	v_exp_f32_e32 v0, v0
	v_exp_f32_e32 v1, v1
	v_exp_f32_e32 v2, v2
	v_exp_f32_e32 v3, v3
	v_pk_fma_f32 v[170:171], v[46:47], v[44:45], v[72:73]
	v_pk_add_f32 v[44:45], v[156:157], -1.0 op_sel_hi:[1,0]
	v_lshlrev_b32_e32 v70, 16, v71
	v_pk_fma_f32 v[42:43], v[42:43], v[44:45], 1.0 op_sel_hi:[1,1,0]
	s_waitcnt vmcnt(0)
	v_sub_f32_e32 v45, v61, v83
	v_sub_f32_e32 v44, v60, v82
	v_and_b32_e32 v71, 0xffff0000, v71
	s_waitcnt lgkmcnt(0)
	v_pk_fma_f32 v[36:37], v[36:37], v[44:45], v[82:83]
	v_lshlrev_b32_e32 v44, 2, v64
	v_mov_b32_e32 v45, v65
	v_sub_f32_e32 v47, v63, v71
	v_sub_f32_e32 v46, v62, v70
	v_lshl_add_u64 v[154:155], v[80:81], 0, v[44:45]
	v_pk_mul_f32 v[40:41], v[40:41], v[168:169]
	v_pk_mul_f32 v[42:43], v[42:43], v[170:171]
	v_pk_fma_f32 v[38:39], v[38:39], v[46:47], v[70:71]
	global_store_dwordx4 v[154:155], v[0:3], off nt
	global_store_dwordx4 v[154:155], v[40:43], off offset:768 nt
	global_store_dwordx4 v[154:155], v[36:39], off offset:1280 nt
	ds_read_b128 v[36:39], v217 offset:4096
	s_nop 0
	ds_read_b128 v[44:47], v217 offset:5120
	ds_read_b128 v[48:51], v217 offset:6144
	ds_read_b128 v[56:59], v217 offset:7168
	s_waitcnt lgkmcnt(0)
	v_mfma_f32_16x16x32_bf16 v[36:39], v[36:39], v[32:35], 0
	s_nop 0
	v_mfma_f32_16x16x32_bf16 v[78:81], v[44:47], v[28:31], 0
	s_nop 0
	v_mfma_f32_16x16x32_bf16 v[36:39], v[48:51], v[24:27], v[36:39]
	ds_read_b128 v[90:93], v208 offset:8256
	ds_read_b128 v[74:77], v208 offset:8512
	ds_read_b128 v[48:51], v208 offset:8768
	ds_read_b128 v[60:63], v208 offset:9024
	ds_read_b128 v[44:47], v208 offset:9280
	ds_read_b128 v[52:55], v208 offset:9536
	ds_read_b128 v[70:73], v208 offset:9792
	ds_read_b128 v[66:69], v208 offset:10048
	s_nop 0
	v_mfma_f32_16x16x32_bf16 v[78:81], v[56:59], v[20:23], v[78:81]
	s_and_saveexec_b64 s[0:1], s[40:41]
	s_xor_b64 s[0:1], exec, s[0:1]
	s_cbranch_execz .LBB0_458
	v_lshl_add_u64 v[56:57], v[64:65], 0, v[150:151]
	v_lshl_add_u64 v[86:87], v[56:57], 2, v[158:159]
	global_load_dwordx4 v[56:59], v[86:87], off offset:64
	global_load_dwordx4 v[82:85], v[86:87], off offset:2112
	v_add_co_u32_e32 v86, vcc, 0x1000, v86
	s_nop 1
	v_addc_co_u32_e32 v87, vcc, 0, v87, vcc
	global_load_dwordx4 v[86:89], v[86:87], off offset:64

.LBB0_462:
	s_or_b64 exec, exec, s[0:1]
	s_waitcnt lgkmcnt(7)
	v_add_f32_e32 v36, v36, v90
	v_max_f32_e64 v90, -v36, 0
	v_mul_f32_e64 v36, |v36|, s87
	v_exp_f32_e32 v36, v36
	s_waitcnt lgkmcnt(6)
	v_add_f32_e32 v74, v78, v74
	v_mul_f32_e32 v74, 0xbfb8aa3b, v74
	v_exp_f32_e32 v74, v74
	v_add_f32_e32 v36, 1.0, v36
	v_cmp_gt_f32_e32 vcc, s2, v36
	v_add_f32_e32 v37, v37, v91
	v_add_f32_e32 v74, 1.0, v74
	v_cndmask_b32_e64 v102, 0, 32, vcc
	v_ldexp_f32 v36, v36, v102
	v_log_f32_e32 v36, v36
	v_rcp_f32_e32 v166, v74
	v_max_f32_e64 v74, -v37, 0
	v_mul_f32_e64 v37, |v37|, s87
	v_exp_f32_e32 v37, v37
	v_mul_f32_e32 v102, 0x3f317217, v36
	s_mov_b32 s20, 0x3f317217
	v_fma_f32 v102, v36, s20, -v102
	v_fmac_f32_e32 v102, 0x3377d1cf, v36
	s_mov_b32 s21, 0x7f800000
	v_fmac_f32_e32 v102, 0x3f317217, v36
	v_cmp_lt_f32_e64 s[0:1], |v36|, s21
	v_add_f32_e32 v37, 1.0, v37
	v_lshlrev_b32_e32 v100, 16, v94
	v_cndmask_b32_e64 v36, v36, v102, s[0:1]
	v_cndmask_b32_e32 v102, 0, v197, vcc
	v_cmp_gt_f32_e32 vcc, s2, v37
	v_and_b32_e32 v101, 0xffff0000, v94
	v_add_f32_e32 v38, v38, v92
	v_cndmask_b32_e64 v78, 0, 32, vcc
	v_ldexp_f32 v37, v37, v78
	v_log_f32_e32 v37, v37
	v_add_f32_e32 v39, v39, v93
	v_sub_f32_e32 v36, v36, v102
	v_add_f32_e32 v36, v90, v36
	v_mul_f32_e32 v78, 0x3f317217, v37
	v_fma_f32 v78, v37, s20, -v78
	v_fmac_f32_e32 v78, 0x3377d1cf, v37
	v_fmac_f32_e32 v78, 0x3f317217, v37
	v_cmp_lt_f32_e64 s[0:1], |v37|, s21
	v_sub_f32_e32 v36, -0.5, v36
	v_mul_f32_e32 v36, 0x3fb8aa3b, v36
	v_cndmask_b32_e64 v37, v37, v78, s[0:1]
	v_cndmask_b32_e32 v78, 0, v197, vcc
	v_sub_f32_e32 v37, v37, v78
	v_add_f32_e32 v37, v74, v37
	v_add_f32_e32 v74, v79, v75
	v_mul_f32_e32 v74, 0xbfb8aa3b, v74
	v_exp_f32_e32 v74, v74
	v_sub_f32_e32 v37, -0.5, v37
	v_mul_f32_e32 v37, 0x3fb8aa3b, v37
	v_exp_f32_e32 v36, v36
	v_add_f32_e32 v74, 1.0, v74
	v_rcp_f32_e32 v167, v74
	s_waitcnt vmcnt(1)
	v_pk_add_f32 v[74:75], v[82:83], v[100:101] neg_lo:[0,1] neg_hi:[0,1]
	v_exp_f32_e32 v37, v37
	s_waitcnt lgkmcnt(1)
	v_pk_fma_f32 v[174:175], v[70:71], v[74:75], v[100:101]
	v_pk_add_f32 v[70:71], v[166:167], -1.0 op_sel_hi:[1,0]
	v_lshlrev_b32_e32 v209, 6, v98
	v_pk_fma_f32 v[60:61], v[60:61], v[70:71], 1.0 op_sel_hi:[1,1,0]
	v_max_f32_e64 v70, -v38, 0
	v_mul_f32_e64 v38, |v38|, s87
	v_exp_f32_e32 v38, v38
	v_lshlrev_b32_e32 v98, 16, v95
	v_and_b32_e32 v99, 0xffff0000, v95
	v_mul_f32_e32 v36, 0xbfb8aa3b, v36
	v_add_f32_e32 v38, 1.0, v38
	v_cmp_gt_f32_e32 vcc, s2, v38
	v_mul_f32_e32 v37, 0xbfb8aa3b, v37
	v_exp_f32_e32 v36, v36
	v_cndmask_b32_e64 v71, 0, 32, vcc
	v_ldexp_f32 v38, v38, v71
	v_log_f32_e32 v38, v38
	v_exp_f32_e32 v37, v37
	v_lshlrev_b32_e32 v94, 16, v96
	v_and_b32_e32 v95, 0xffff0000, v96
	v_mul_f32_e32 v71, 0x3f317217, v38
	v_fma_f32 v71, v38, s20, -v71
	v_fmac_f32_e32 v71, 0x3377d1cf, v38
	v_fmac_f32_e32 v71, 0x3f317217, v38
	v_cmp_lt_f32_e64 s[0:1], |v38|, s21
	v_lshlrev_b32_e32 v96, 16, v97
	v_and_b32_e32 v97, 0xffff0000, v97
	v_cndmask_b32_e64 v38, v38, v71, s[0:1]
	v_cndmask_b32_e32 v71, 0, v197, vcc
	v_sub_f32_e32 v38, v38, v71
	v_add_f32_e32 v38, v70, v38
	v_add_f32_e32 v70, v80, v76
	v_mul_f32_e32 v70, 0xbfb8aa3b, v70
	v_exp_f32_e32 v70, v70
	v_sub_f32_e32 v38, -0.5, v38
	v_mul_f32_e32 v38, 0x3fb8aa3b, v38
	v_exp_f32_e32 v38, v38
	v_add_f32_e32 v70, 1.0, v70
	v_rcp_f32_e32 v172, v70
	v_max_f32_e64 v70, -v39, 0
	v_mul_f32_e64 v39, |v39|, s87
	v_exp_f32_e32 v39, v39
	v_mul_f32_e32 v38, 0xbfb8aa3b, v38
	v_exp_f32_e32 v38, v38
	v_pk_mul_f32 v[60:61], v[60:61], v[174:175]
	v_add_f32_e32 v39, 1.0, v39
	v_cmp_gt_f32_e32 vcc, s2, v39
	s_nop 1
	v_cndmask_b32_e64 v71, 0, 32, vcc
	v_ldexp_f32 v39, v39, v71
	v_log_f32_e32 v39, v39
	s_nop 0
	v_mul_f32_e32 v71, 0x3f317217, v39
	v_fma_f32 v71, v39, s20, -v71
	v_fmac_f32_e32 v71, 0x3377d1cf, v39
	v_fmac_f32_e32 v71, 0x3f317217, v39
	v_cmp_lt_f32_e64 s[0:1], |v39|, s21
	s_nop 1
	v_cndmask_b32_e64 v39, v39, v71, s[0:1]
	v_cndmask_b32_e32 v71, 0, v197, vcc
	v_sub_f32_e32 v39, v39, v71
	v_add_f32_e32 v39, v70, v39
	v_add_f32_e32 v70, v81, v77
	v_mul_f32_e32 v70, 0xbfb8aa3b, v70
	v_exp_f32_e32 v70, v70
	v_sub_f32_e32 v39, -0.5, v39
	v_mul_f32_e32 v39, 0x3fb8aa3b, v39
	v_exp_f32_e32 v39, v39
	v_add_f32_e32 v70, 1.0, v70
	v_rcp_f32_e32 v173, v70
	v_pk_add_f32 v[70:71], v[84:85], v[98:99] neg_lo:[0,1] neg_hi:[0,1]
	v_mul_f32_e32 v39, 0xbfb8aa3b, v39
	v_exp_f32_e32 v39, v39
	v_pk_fma_f32 v[180:181], v[72:73], v[70:71], v[98:99]
	v_pk_add_f32 v[70:71], v[172:173], -1.0 op_sel_hi:[1,0]
	s_waitcnt vmcnt(0)
	v_sub_f32_e32 v73, v89, v97
	v_pk_fma_f32 v[62:63], v[62:63], v[70:71], 1.0 op_sel_hi:[1,1,0]
	v_sub_f32_e32 v71, v87, v95
	v_sub_f32_e32 v70, v86, v94
	v_sub_f32_e32 v72, v88, v96
	s_waitcnt lgkmcnt(0)
	v_pk_fma_f32 v[66:67], v[66:67], v[70:71], v[94:95]
	v_pk_mul_f32 v[62:63], v[62:63], v[180:181]
	v_pk_fma_f32 v[68:69], v[68:69], v[72:73], v[96:97]
	global_store_dwordx4 v[154:155], v[36:39], off offset:64 nt
	global_store_dwordx4 v[154:155], v[60:63], off offset:832 nt
	global_store_dwordx4 v[154:155], v[66:69], off offset:1344 nt
	s_nop 1
	v_lshl_or_b32 v66, v209, 1, v198
	v_mov_b32_e32 v67, v65
	v_lshl_add_u64 v[74:75], v[160:161], 0, v[66:67]
	v_lshl_add_u64 v[78:79], v[162:163], 0, v[66:67]
	ds_read_b128 v[66:69], v217 offset:8192
	ds_read_b128 v[70:73], v217 offset:9216
	s_nop 0
	ds_read_b128 v[74:77], v217 offset:10240
	s_nop 0
	ds_read_b128 v[78:81], v217 offset:11264
	s_waitcnt lgkmcnt(0)
	v_mfma_f32_16x16x32_bf16 v[66:69], v[66:69], v[32:35], 0
	s_nop 0
	v_mfma_f32_16x16x32_bf16 v[70:73], v[70:73], v[28:31], 0
	s_nop 0
	v_mfma_f32_16x16x32_bf16 v[66:69], v[74:77], v[24:27], v[66:69]
	s_nop 0
	v_mfma_f32_16x16x32_bf16 v[98:101], v[78:81], v[20:23], v[70:73]
	ds_read_b128 v[110:113], v208 offset:8320
	ds_read_b128 v[102:105], v208 offset:8576
	ds_read_b128 v[74:77], v208 offset:8832
	ds_read_b128 v[90:93], v208 offset:9088
	ds_read_b128 v[70:73], v208 offset:9344
	ds_read_b128 v[78:81], v208 offset:9600
	ds_read_b128 v[94:97], v208 offset:9856
	ds_read_b128 v[86:89], v208 offset:10112
	s_and_saveexec_b64 s[0:1], s[40:41]
	s_xor_b64 s[0:1], exec, s[0:1]
	s_cbranch_execz .LBB0_464
	v_lshl_add_u64 v[82:83], v[64:65], 0, v[150:151]
	v_lshl_add_u64 v[114:115], v[82:83], 2, v[158:159]
	global_load_dwordx4 v[82:85], v[114:115], off offset:128
	global_load_dwordx4 v[106:109], v[114:115], off offset:2176
	v_add_co_u32_e32 v114, vcc, 0x1000, v114
	s_nop 1
	v_addc_co_u32_e32 v115, vcc, 0, v115, vcc
	global_load_dwordx4 v[114:117], v[114:115], off offset:128

.LBB0_468:
	s_or_b64 exec, exec, s[0:1]
	s_waitcnt lgkmcnt(7)
	v_add_f32_e32 v66, v66, v110
	v_mul_f32_e64 v110, |v66|, s87
	v_exp_f32_e32 v110, v110
	s_mov_b32 s20, 0x3f317217
	s_mov_b32 s21, 0x7f800000
	v_max_f32_e64 v66, -v66, 0
	v_add_f32_e32 v110, 1.0, v110
	v_cmp_gt_f32_e32 vcc, s2, v110
	v_add_f32_e32 v67, v67, v111
	s_waitcnt lgkmcnt(6)
	v_add_f32_e32 v98, v98, v102
	v_cndmask_b32_e64 v124, 0, 32, vcc
	v_ldexp_f32 v110, v110, v124
	v_log_f32_e32 v110, v110
	v_mul_f32_e32 v98, 0xbfb8aa3b, v98
	v_add_f32_e32 v99, v99, v103
	v_exp_f32_e32 v98, v98
	v_mul_f32_e32 v124, 0x3f317217, v110
	v_fma_f32 v124, v110, s20, -v124
	v_fmac_f32_e32 v124, 0x3377d1cf, v110
	v_fmac_f32_e32 v124, 0x3f317217, v110
	v_cmp_lt_f32_e64 s[0:1], |v110|, s21
	v_mul_f32_e32 v99, 0xbfb8aa3b, v99
	v_exp_f32_e32 v99, v99
	v_cndmask_b32_e64 v110, v110, v124, s[0:1]
	v_cndmask_b32_e32 v124, 0, v197, vcc
	v_sub_f32_e32 v110, v110, v124
	v_add_f32_e32 v66, v66, v110
	v_mul_f32_e64 v110, |v67|, s87
	v_exp_f32_e32 v110, v110
	v_add_f32_e32 v98, 1.0, v98
	v_rcp_f32_e32 v176, v98
	v_add_f32_e32 v98, 1.0, v99
	v_add_f32_e32 v102, 1.0, v110
	v_cmp_gt_f32_e32 vcc, s2, v102
	v_add_f32_e32 v68, v68, v112
	v_max_f32_e64 v67, -v67, 0
	v_cndmask_b32_e64 v110, 0, 32, vcc
	v_ldexp_f32 v102, v102, v110
	v_log_f32_e32 v102, v102
	v_rcp_f32_e32 v177, v98
	v_mul_f32_e64 v98, |v68|, s87
	v_lshlrev_b32_e32 v122, 16, v120
	v_mul_f32_e32 v110, 0x3f317217, v102
	v_fma_f32 v110, v102, s20, -v110
	v_fmac_f32_e32 v110, 0x3377d1cf, v102
	v_fmac_f32_e32 v110, 0x3f317217, v102
	v_cmp_lt_f32_e64 s[0:1], |v102|, s21
	v_and_b32_e32 v123, 0xffff0000, v120
	v_max_f32_e64 v68, -v68, 0
	v_cndmask_b32_e64 v102, v102, v110, s[0:1]
	v_cndmask_b32_e32 v110, 0, v197, vcc
	v_sub_f32_e32 v102, v102, v110
	v_add_f32_e32 v67, v67, v102
	v_exp_f32_e32 v102, v98
	s_waitcnt vmcnt(1)
	v_pk_add_f32 v[98:99], v[106:107], v[122:123] neg_lo:[0,1] neg_hi:[0,1]
	v_add_f32_e32 v69, v69, v113
	s_waitcnt lgkmcnt(1)
	v_pk_fma_f32 v[182:183], v[94:95], v[98:99], v[122:123]
	v_add_f32_e32 v98, 1.0, v102
	v_cmp_gt_f32_e32 vcc, s2, v98
	v_pk_add_f32 v[94:95], v[176:177], -1.0 op_sel_hi:[1,0]
	v_sub_f32_e32 v66, -0.5, v66
	v_cndmask_b32_e64 v99, 0, 32, vcc
	v_ldexp_f32 v98, v98, v99
	v_log_f32_e32 v98, v98
	v_pk_fma_f32 v[90:91], v[90:91], v[94:95], 1.0 op_sel_hi:[1,1,0]
	v_sub_f32_e32 v67, -0.5, v67
	v_pk_mul_f32 v[122:123], v[90:91], v[182:183]
	v_mul_f32_e32 v90, 0x3f317217, v98
	v_fma_f32 v90, v98, s20, -v90
	v_fmac_f32_e32 v90, 0x3377d1cf, v98
	v_fmac_f32_e32 v90, 0x3f317217, v98
	v_cmp_lt_f32_e64 s[0:1], |v98|, s21
	v_cndmask_b32_e32 v91, 0, v197, vcc
	v_mul_f32_e32 v66, 0x3fb8aa3b, v66
	v_cndmask_b32_e64 v90, v98, v90, s[0:1]
	v_sub_f32_e32 v90, v90, v91
	v_add_f32_e32 v68, v68, v90
	v_mul_f32_e64 v90, |v69|, s87
	v_exp_f32_e32 v90, v90
	v_max_f32_e64 v69, -v69, 0
	v_add_f32_e32 v91, v100, v104
	v_mul_f32_e32 v91, 0xbfb8aa3b, v91
	v_add_f32_e32 v90, 1.0, v90
	v_cmp_gt_f32_e32 vcc, s2, v90
	v_exp_f32_e32 v91, v91
	v_sub_f32_e32 v68, -0.5, v68
	v_cndmask_b32_e64 v94, 0, 32, vcc
	v_ldexp_f32 v90, v90, v94
	v_log_f32_e32 v90, v90
	v_mul_f32_e32 v67, 0x3fb8aa3b, v67
	v_mul_f32_e32 v68, 0x3fb8aa3b, v68
	v_exp_f32_e32 v66, v66
	v_mul_f32_e32 v94, 0x3f317217, v90
	v_fma_f32 v94, v90, s20, -v94
	v_fmac_f32_e32 v94, 0x3377d1cf, v90
	v_fmac_f32_e32 v94, 0x3f317217, v90
	v_cmp_lt_f32_e64 s[0:1], |v90|, s21
	v_exp_f32_e32 v67, v67
	v_exp_f32_e32 v68, v68
	v_cndmask_b32_e64 v90, v90, v94, s[0:1]
	v_cndmask_b32_e32 v94, 0, v197, vcc
	v_sub_f32_e32 v90, v90, v94
	v_add_f32_e32 v69, v69, v90
	v_add_f32_e32 v90, v101, v105
	v_mul_f32_e32 v90, 0xbfb8aa3b, v90
	v_exp_f32_e32 v90, v90
	v_sub_f32_e32 v69, -0.5, v69
	v_mul_f32_e32 v69, 0x3fb8aa3b, v69
	v_exp_f32_e32 v69, v69
	v_add_f32_e32 v91, 1.0, v91
	v_add_f32_e32 v90, 1.0, v90
	v_rcp_f32_e32 v178, v91
	v_rcp_f32_e32 v179, v90
	v_lshlrev_b32_e32 v120, 16, v121
	v_and_b32_e32 v121, 0xffff0000, v121
	v_mul_f32_e32 v66, 0xbfb8aa3b, v66
	v_mul_f32_e32 v67, 0xbfb8aa3b, v67
	v_mul_f32_e32 v68, 0xbfb8aa3b, v68
	v_mul_f32_e32 v69, 0xbfb8aa3b, v69
	v_pk_add_f32 v[90:91], v[108:109], v[120:121] neg_lo:[0,1] neg_hi:[0,1]
	v_exp_f32_e32 v66, v66
	v_exp_f32_e32 v67, v67
	v_exp_f32_e32 v68, v68
	v_exp_f32_e32 v69, v69
	v_pk_fma_f32 v[184:185], v[96:97], v[90:91], v[120:121]
	v_pk_add_f32 v[90:91], v[178:179], -1.0 op_sel_hi:[1,0]
	v_lshlrev_b32_e32 v210, 16, v118
	v_and_b32_e32 v211, 0xffff0000, v118
	v_pk_fma_f32 v[90:91], v[92:93], v[90:91], 1.0 op_sel_hi:[1,1,0]
	v_lshlrev_b32_e32 v118, 16, v119
	v_and_b32_e32 v119, 0xffff0000, v119
	v_pk_mul_f32 v[124:125], v[90:91], v[184:185]
	s_waitcnt vmcnt(0)
	v_sub_f32_e32 v91, v115, v211
	v_sub_f32_e32 v90, v114, v210
	v_sub_f32_e32 v93, v117, v119
	v_sub_f32_e32 v92, v116, v118
	s_waitcnt lgkmcnt(0)
	v_pk_fma_f32 v[86:87], v[86:87], v[90:91], v[210:211]
	v_lshl_or_b32 v90, v209, 1, v199
	v_mov_b32_e32 v91, v65
	v_pk_fma_f32 v[88:89], v[88:89], v[92:93], v[118:119]
	global_store_dwordx4 v[154:155], v[66:69], off offset:128 nt
	global_store_dwordx4 v[154:155], v[122:125], off offset:896 nt
	global_store_dwordx4 v[154:155], v[86:89], off offset:1408 nt
	v_lshl_add_u64 v[94:95], v[160:161], 0, v[90:91]
	s_nop 0
	v_lshl_add_u64 v[98:99], v[162:163], 0, v[90:91]
	s_nop 0
	s_nop 0
	s_nop 0
	s_nop 0
	v_mfma_f32_16x16x32_bf16 v[106:109], a[4:7], v[28:31], 0
	s_nop 0
	v_mfma_f32_16x16x32_bf16 v[32:35], a[0:3], v[32:35], 0
	s_nop 0
	v_mfma_f32_16x16x32_bf16 v[114:117], a[8:11], v[24:27], v[32:35]
	ds_read_b128 v[118:121], v208 offset:8384
	ds_read_b128 v[102:105], v208 offset:8640
	ds_read_b128 v[86:89], v208 offset:8896
	ds_read_b128 v[90:93], v208 offset:9152
	ds_read_b128 v[28:31], v208 offset:9408
	s_nop 0
	ds_read_b128 v[32:35], v208 offset:9664
	ds_read_b128 v[94:97], v208 offset:9920
	ds_read_b128 v[24:27], v208 offset:10176
	s_nop 0
	v_mfma_f32_16x16x32_bf16 v[106:109], a[12:15], v[20:23], v[106:109]
	s_and_saveexec_b64 s[0:1], s[40:41]
	s_xor_b64 s[0:1], exec, s[0:1]
	s_cbranch_execz .LBB0_470
	v_lshl_add_u64 v[20:21], v[64:65], 0, v[150:151]
	v_lshl_add_u64 v[98:99], v[20:21], 2, v[158:159]
	global_load_dwordx4 v[20:23], v[98:99], off offset:192
	global_load_dwordx4 v[110:113], v[98:99], off offset:2240
	v_add_co_u32_e32 v98, vcc, 0x1000, v98
	s_nop 1
	v_addc_co_u32_e32 v99, vcc, 0, v99, vcc
	global_load_dwordx4 v[98:101], v[98:99], off offset:192

	.amdhsa_kernel _Z4mega6Params
		.amdhsa_group_segment_fixed_size 0
		.amdhsa_private_segment_fixed_size 0
		.amdhsa_kernarg_size 488
		.amdhsa_user_sgpr_count 2
		.amdhsa_user_sgpr_dispatch_ptr 0
		.amdhsa_user_sgpr_queue_ptr 0
		.amdhsa_user_sgpr_kernarg_segment_ptr 1
		.amdhsa_user_sgpr_dispatch_id 0
		.amdhsa_user_sgpr_kernarg_preload_length 0
		.amdhsa_user_sgpr_kernarg_preload_offset 0
		.amdhsa_user_sgpr_private_segment_size 0
		.amdhsa_uses_dynamic_stack 0
		.amdhsa_enable_private_segment 0
		.amdhsa_system_sgpr_workgroup_id_x 1
		.amdhsa_system_sgpr_workgroup_id_y 0
		.amdhsa_system_sgpr_workgroup_id_z 0
		.amdhsa_system_sgpr_workgroup_info 0
		.amdhsa_system_vgpr_workitem_id 2
		.amdhsa_next_free_vgpr 236
		.amdhsa_next_free_sgpr 100
		.amdhsa_accum_offset 220
		.amdhsa_reserve_vcc 1
		.amdhsa_float_round_mode_32 0
		.amdhsa_float_round_mode_16_64 0
		.amdhsa_float_denorm_mode_32 3
		.amdhsa_float_denorm_mode_16_64 3
		.amdhsa_dx10_clamp 1
		.amdhsa_ieee_mode 1
		.amdhsa_fp16_overflow 0
		.amdhsa_tg_split 0
		.amdhsa_exception_fp_ieee_invalid_op 0
		.amdhsa_exception_fp_denorm_src 0
		.amdhsa_exception_fp_ieee_div_zero 0
		.amdhsa_exception_fp_ieee_overflow 0
		.amdhsa_exception_fp_ieee_underflow 0
		.amdhsa_exception_fp_ieee_inexact 0
		.amdhsa_exception_int_div_zero 0
	.end_amdhsa_kernel

amdhsa.kernels:
  - .agpr_count:     16
    .args:
      - .offset:         0
        .size:           232
        .value_kind:     by_value
      - .offset:         232
        .size:           4
        .value_kind:     hidden_block_count_x
      - .offset:         236
        .size:           4
        .value_kind:     hidden_block_count_y
      - .offset:         240
        .size:           4
        .value_kind:     hidden_block_count_z
      - .offset:         244
        .size:           2
        .value_kind:     hidden_group_size_x
      - .offset:         246
        .size:           2
        .value_kind:     hidden_group_size_y
      - .offset:         248
        .size:           2
        .value_kind:     hidden_group_size_z
      - .offset:         250
        .size:           2
        .value_kind:     hidden_remainder_x
      - .offset:         252
        .size:           2
        .value_kind:     hidden_remainder_y
      - .offset:         254
        .size:           2
        .value_kind:     hidden_remainder_z
      - .offset:         272
        .size:           8
        .value_kind:     hidden_global_offset_x
      - .offset:         280
        .size:           8
        .value_kind:     hidden_global_offset_y
      - .offset:         288
        .size:           8
        .value_kind:     hidden_global_offset_z
      - .offset:         296
        .size:           2
        .value_kind:     hidden_grid_dims
      - .offset:         320
        .size:           8
        .value_kind:     hidden_multigrid_sync_arg
      - .offset:         352
        .size:           4
        .value_kind:     hidden_dynamic_lds_size
    .group_segment_fixed_size: 0
    .kernarg_segment_align: 8
    .kernarg_segment_size: 488
    .language:       OpenCL C
    .language_version:
      - 2
      - 0
    .max_flat_workgroup_size: 512
    .name:           _Z4mega6Params
    .private_segment_fixed_size: 0
    .sgpr_count:     106
    .sgpr_spill_count: 308
    .symbol:         _Z4mega6Params.kd
    .uniform_work_group_size: 1
    .uses_dynamic_stack: false
    .vgpr_count:     220
    .vgpr_spill_count: 0
    .wavefront_size: 64
